# dilated attention: K fragments (first 24 QK MFMAs) and V fragments (first 30 PV MFMAs) read one MFMA ahead into a spare register quad instead of read-wait-MFMA
# speedup vs baseline: 1.0109x; 1.0074x over previous
.LBB0_100:
	v_add_co_u32_e32 v8, vcc, 0x8000, v4
	s_mov_b32 s1, 0x10000
	s_nop 0
	v_addc_co_u32_e32 v9, vcc, 0, v5, vcc
	global_load_dwordx4 v[146:149], v[8:9], off
	v_add_co_u32_e32 v8, vcc, 0xa000, v4
	s_nop 1
	v_addc_co_u32_e32 v9, vcc, 0, v5, vcc
	global_load_dwordx4 v[150:153], v[8:9], off
	v_add_co_u32_e32 v8, vcc, 0xc000, v4
	s_nop 1
	v_addc_co_u32_e32 v9, vcc, 0, v5, vcc
	global_load_dwordx4 v[154:157], v[8:9], off
	v_add_co_u32_e32 v8, vcc, 0xe000, v4
	s_nop 1
	v_addc_co_u32_e32 v9, vcc, 0, v5, vcc
	global_load_dwordx4 v[158:161], v[8:9], off
	v_add_co_u32_e32 v8, vcc, s1, v4
	s_add_i32 s1, 0, 0x18000
	s_nop 0
	v_addc_co_u32_e32 v9, vcc, 0, v5, vcc
	global_load_dwordx4 v[162:165], v[8:9], off
	v_add_co_u32_e32 v8, vcc, 0x12000, v4
	s_cmp_eq_u32 s81, 0
	s_nop 0
	v_addc_co_u32_e32 v9, vcc, 0, v5, vcc
	global_load_dwordx4 v[166:169], v[8:9], off
	v_add_co_u32_e32 v8, vcc, 0x14000, v4
	s_cselect_b64 s[6:7], -1, 0
	s_nop 0
	v_addc_co_u32_e32 v9, vcc, 0, v5, vcc
	v_add_co_u32_e32 v4, vcc, 0x16000, v4
	global_load_dwordx4 v[170:173], v[8:9], off
	s_nop 0
	v_addc_co_u32_e32 v5, vcc, 0, v5, vcc
	global_load_dwordx4 v[174:177], v[4:5], off
	v_lshlrev_b32_e32 v4, 2, v6
	v_and_b32_e32 v4, 12, v4
	v_bfe_u32 v5, v6, 2, 2
	v_or_b32_e32 v8, v4, v5
	v_bitop3_b32 v4, v4, v226, v5 bitop3:0x36
	v_lshl_add_u32 v9, v227, 8, s80
	v_lshl_add_u32 v10, v4, 4, v9
	v_bitop3_b32 v232, v226, v8, 2 bitop3:0x36
	v_lshl_add_u32 v232, v232, 4, v9
	v_bitop3_b32 v236, v226, v8, 4 bitop3:0x36
	v_lshl_add_u32 v236, v236, 4, v9
	v_bitop3_b32 v237, v226, v8, 6 bitop3:0x36
	v_lshl_add_u32 v237, v237, 4, v9
	v_bitop3_b32 v238, v226, v8, 8 bitop3:0x36
	v_lshl_add_u32 v238, v238, 4, v9
	v_bitop3_b32 v239, v226, v8, 10 bitop3:0x36
	v_lshl_add_u32 v239, v239, 4, v9
	v_bitop3_b32 v240, v226, v8, 12 bitop3:0x36
	v_lshl_add_u32 v240, v240, 4, v9
	v_bitop3_b32 v100, v226, v8, 14 bitop3:0x36
	v_lshl_add_u32 v100, v100, 4, v9
	s_and_b64 s[28:29], s[12:13], s[6:7]
	s_and_b64 vcc, exec, s[28:29]
	ds_read_b128 v[4:7], v10
	ds_read_b128 v[244:247], v232
	s_waitcnt vmcnt(15) lgkmcnt(1)
	v_mfma_f32_32x32x16_bf16 v[64:79], v[4:7], v[0:3], 0
	ds_read_b128 v[4:7], v236
	s_waitcnt vmcnt(14) lgkmcnt(1)
	v_mfma_f32_32x32x16_bf16 v[64:79], v[244:247], v[202:205], v[64:79]
	ds_read_b128 v[244:247], v237
	s_waitcnt vmcnt(13) lgkmcnt(1)
	v_mfma_f32_32x32x16_bf16 v[64:79], v[4:7], v[198:201], v[64:79]
	ds_read_b128 v[4:7], v238
	s_waitcnt vmcnt(12) lgkmcnt(1)
	v_mfma_f32_32x32x16_bf16 v[64:79], v[244:247], v[194:197], v[64:79]
	ds_read_b128 v[244:247], v239
	s_waitcnt vmcnt(11) lgkmcnt(1)
	v_mfma_f32_32x32x16_bf16 v[64:79], v[4:7], v[190:193], v[64:79]
	ds_read_b128 v[4:7], v240
	s_waitcnt vmcnt(10) lgkmcnt(1)
	v_mfma_f32_32x32x16_bf16 v[64:79], v[244:247], v[186:189], v[64:79]
	ds_read_b128 v[244:247], v100
	s_waitcnt vmcnt(9) lgkmcnt(1)
	v_mfma_f32_32x32x16_bf16 v[64:79], v[4:7], v[182:185], v[64:79]
	ds_read_b128 v[4:7], v10 offset:8192
	s_waitcnt vmcnt(8) lgkmcnt(1)
	v_mfma_f32_32x32x16_bf16 v[64:79], v[244:247], v[178:181], v[64:79]
	ds_read_b128 v[244:247], v232 offset:8192
	s_waitcnt lgkmcnt(1)
	v_mfma_f32_32x32x16_bf16 v[48:63], v[4:7], v[0:3], 0
	ds_read_b128 v[4:7], v236 offset:8192
	s_waitcnt lgkmcnt(1)
	v_mfma_f32_32x32x16_bf16 v[48:63], v[244:247], v[202:205], v[48:63]
	ds_read_b128 v[244:247], v237 offset:8192
	s_waitcnt lgkmcnt(1)
	v_mfma_f32_32x32x16_bf16 v[48:63], v[4:7], v[198:201], v[48:63]
	ds_read_b128 v[4:7], v238 offset:8192
	s_waitcnt lgkmcnt(1)
	v_mfma_f32_32x32x16_bf16 v[48:63], v[244:247], v[194:197], v[48:63]
	ds_read_b128 v[244:247], v239 offset:8192
	s_waitcnt lgkmcnt(1)
	v_mfma_f32_32x32x16_bf16 v[48:63], v[4:7], v[190:193], v[48:63]
	ds_read_b128 v[4:7], v240 offset:8192
	s_waitcnt lgkmcnt(1)
	v_mfma_f32_32x32x16_bf16 v[48:63], v[244:247], v[186:189], v[48:63]
	ds_read_b128 v[244:247], v100 offset:8192
	s_waitcnt lgkmcnt(1)
	v_mfma_f32_32x32x16_bf16 v[48:63], v[4:7], v[182:185], v[48:63]
	ds_read_b128 v[4:7], v10 offset:16384
	s_waitcnt lgkmcnt(1)
	v_mfma_f32_32x32x16_bf16 v[48:63], v[244:247], v[178:181], v[48:63]
	ds_read_b128 v[244:247], v232 offset:16384
	s_waitcnt lgkmcnt(1)
	v_mfma_f32_32x32x16_bf16 v[32:47], v[4:7], v[0:3], 0
	ds_read_b128 v[4:7], v236 offset:16384
	s_waitcnt lgkmcnt(1)
	v_mfma_f32_32x32x16_bf16 v[32:47], v[244:247], v[202:205], v[32:47]
	ds_read_b128 v[244:247], v237 offset:16384
	s_waitcnt lgkmcnt(1)
	v_mfma_f32_32x32x16_bf16 v[32:47], v[4:7], v[198:201], v[32:47]
	ds_read_b128 v[4:7], v238 offset:16384
	s_waitcnt lgkmcnt(1)
	v_mfma_f32_32x32x16_bf16 v[32:47], v[244:247], v[194:197], v[32:47]
	ds_read_b128 v[244:247], v239 offset:16384
	s_waitcnt lgkmcnt(1)
	v_mfma_f32_32x32x16_bf16 v[32:47], v[4:7], v[190:193], v[32:47]
	ds_read_b128 v[4:7], v240 offset:16384
	s_waitcnt lgkmcnt(1)
	v_mfma_f32_32x32x16_bf16 v[32:47], v[244:247], v[186:189], v[32:47]
	ds_read_b128 v[244:247], v100 offset:16384
	s_waitcnt lgkmcnt(1)
	v_mfma_f32_32x32x16_bf16 v[32:47], v[4:7], v[182:185], v[32:47]
	s_waitcnt lgkmcnt(0)
	v_mfma_f32_32x32x16_bf16 v[32:47], v[244:247], v[178:181], v[32:47]
	ds_read_b128 v[4:7], v10 offset:24576
	s_waitcnt lgkmcnt(0)
	v_mfma_f32_32x32x16_bf16 v[16:31], v[4:7], v[0:3], 0
	ds_read_b128 v[4:7], v232 offset:24576
	ds_read_b128 v[232:235], v232 offset:32768
	s_waitcnt lgkmcnt(1)
	v_mfma_f32_32x32x16_bf16 v[16:31], v[4:7], v[202:205], v[16:31]
	ds_read_b128 v[4:7], v236 offset:24576
	s_waitcnt lgkmcnt(0)
	v_mfma_f32_32x32x16_bf16 v[16:31], v[4:7], v[198:201], v[16:31]
	ds_read_b128 v[4:7], v237 offset:24576
	s_waitcnt lgkmcnt(0)
	v_mfma_f32_32x32x16_bf16 v[16:31], v[4:7], v[194:197], v[16:31]
	ds_read_b128 v[4:7], v238 offset:24576
	s_waitcnt lgkmcnt(0)
	v_mfma_f32_32x32x16_bf16 v[16:31], v[4:7], v[190:193], v[16:31]
	ds_read_b128 v[4:7], v239 offset:24576
	s_waitcnt lgkmcnt(0)
	v_mfma_f32_32x32x16_bf16 v[16:31], v[4:7], v[186:189], v[16:31]
	ds_read_b128 v[4:7], v240 offset:24576
	s_waitcnt lgkmcnt(0)
	v_mfma_f32_32x32x16_bf16 v[16:31], v[4:7], v[182:185], v[16:31]
	ds_read_b128 v[4:7], v100 offset:24576
	s_waitcnt lgkmcnt(0)
	v_mfma_f32_32x32x16_bf16 v[16:31], v[4:7], v[178:181], v[16:31]
	ds_read_b128 v[4:7], v10 offset:32768
	s_waitcnt lgkmcnt(0)
	v_mfma_f32_32x32x16_bf16 v[0:15], v[4:7], v[0:3], 0
	v_mfma_f32_32x32x16_bf16 v[0:15], v[232:235], v[202:205], v[0:15]
	ds_read_b128 v[202:205], v236 offset:32768
	s_waitcnt lgkmcnt(0)
	v_mfma_f32_32x32x16_bf16 v[0:15], v[202:205], v[198:201], v[0:15]
	ds_read_b128 v[198:201], v237 offset:32768
	v_mov_b32_e32 v202, 0xff800000
	s_waitcnt lgkmcnt(0)
	v_mfma_f32_32x32x16_bf16 v[0:15], v[198:201], v[194:197], v[0:15]
	ds_read_b128 v[194:197], v238 offset:32768
	s_waitcnt lgkmcnt(0)
	v_mfma_f32_32x32x16_bf16 v[0:15], v[194:197], v[190:193], v[0:15]
	ds_read_b128 v[190:193], v239 offset:32768
	v_mov_b32_e32 v195, 0xff800000
	v_mov_b32_e32 v194, 0xff800000
	v_mov_b32_e32 v197, 0xff800000
	v_mov_b32_e32 v196, 0xff800000
	s_waitcnt lgkmcnt(0)
	v_mfma_f32_32x32x16_bf16 v[0:15], v[190:193], v[186:189], v[0:15]
	ds_read_b128 v[186:189], v240 offset:32768
	v_mov_b32_e32 v190, 0xff800000
	v_mov_b32_e32 v191, 0xff800000
	v_mov_b32_e32 v193, 0xff800000
	v_mov_b32_e32 v192, 0xff800000
	s_waitcnt lgkmcnt(0)
	v_mfma_f32_32x32x16_bf16 v[0:15], v[186:189], v[182:185], v[0:15]
	ds_read_b128 v[182:185], v100 offset:32768
	v_mov_b32_e32 v100, 0xff800000
	v_mov_b32_e32 v186, 0xff800000
	v_mov_b32_e32 v189, 0xff800000
	v_mov_b32_e32 v188, 0xff800000
	s_waitcnt lgkmcnt(0)
	v_mfma_f32_32x32x16_bf16 v[0:15], v[182:185], v[178:181], v[0:15]
	v_lshlrev_b32_e32 v180, 2, v226
	v_sub_u32_e32 v181, v227, v180
	v_lshl_add_u32 v187, v181, 2, s1
	v_mov_b32_e32 v178, 0xff800000
	v_mov_b32_e32 v182, 0xff800000
	v_mov_b32_e32 v184, 0xff800000
	v_mov_b32_e32 v183, 0xff800000
	v_mov_b32_e32 v185, 0xff800000
	s_cbranch_vccnz .LBB0_102
	ds_read2_b32 v[182:183], v187 offset0:159 offset1:160
	v_cmp_gt_i32_e32 vcc, 2, v181
	s_mov_b32 s1, 0xff800000
	s_waitcnt lgkmcnt(0)
	v_pk_add_f32 v[64:65], v[64:65], v[182:183] op_sel:[0,1] op_sel_hi:[1,0]
	s_nop 0
	v_cndmask_b32_e32 v100, v220, v65, vcc
	v_cmp_gt_i32_e32 vcc, 1, v181
	s_nop 1
	v_cndmask_b32_e32 v182, v220, v64, vcc
	ds_read2_b32 v[64:65], v187 offset0:157 offset1:158
	v_cmp_gt_i32_e32 vcc, 4, v181
	v_max3_f32 v179, v182, s1, v100
	s_waitcnt lgkmcnt(0)
	v_pk_add_f32 v[64:65], v[66:67], v[64:65] op_sel:[0,1] op_sel_hi:[1,0]
	s_nop 0
	v_cndmask_b32_e32 v183, v220, v65, vcc
	v_cmp_gt_i32_e32 vcc, 3, v181
	s_nop 1
	v_cndmask_b32_e32 v184, v220, v64, vcc
	ds_read2_b32 v[64:65], v187 offset0:151 offset1:152
	v_cmp_gt_i32_e32 vcc, 10, v181
	v_max3_f32 v66, v179, v184, v183
	s_waitcnt lgkmcnt(0)
	v_pk_add_f32 v[64:65], v[68:69], v[64:65] op_sel:[0,1] op_sel_hi:[1,0]
	s_nop 0
	v_cndmask_b32_e32 v185, v220, v65, vcc
	v_cmp_gt_i32_e32 vcc, 9, v181
	s_nop 1
	v_cndmask_b32_e32 v186, v220, v64, vcc
	ds_read2_b32 v[64:65], v187 offset0:149 offset1:150
	v_cmp_gt_i32_e32 vcc, 12, v181
	v_max3_f32 v66, v66, v186, v185
	s_waitcnt lgkmcnt(0)
	v_pk_add_f32 v[64:65], v[70:71], v[64:65] op_sel:[0,1] op_sel_hi:[1,0]
	s_nop 0
	v_cndmask_b32_e32 v188, v220, v65, vcc
	v_cmp_gt_i32_e32 vcc, 11, v181
	s_nop 1
	v_cndmask_b32_e32 v189, v220, v64, vcc
	ds_read2_b32 v[64:65], v187 offset0:143 offset1:144
	v_cmp_gt_i32_e32 vcc, 18, v181
	v_max3_f32 v66, v66, v189, v188
	s_waitcnt lgkmcnt(0)
	v_pk_add_f32 v[64:65], v[72:73], v[64:65] op_sel:[0,1] op_sel_hi:[1,0]
	s_nop 0
	v_cndmask_b32_e32 v191, v220, v65, vcc
	v_cmp_gt_i32_e32 vcc, 17, v181
	s_nop 1
	v_cndmask_b32_e32 v190, v220, v64, vcc
	ds_read2_b32 v[64:65], v187 offset0:141 offset1:142
	v_cmp_gt_i32_e32 vcc, 20, v181
	v_max3_f32 v66, v66, v190, v191
	s_waitcnt lgkmcnt(0)
	v_pk_add_f32 v[64:65], v[74:75], v[64:65] op_sel:[0,1] op_sel_hi:[1,0]
	s_nop 0
	v_cndmask_b32_e32 v192, v220, v65, vcc
	v_cmp_gt_i32_e32 vcc, 19, v181
	s_nop 1
	v_cndmask_b32_e32 v193, v220, v64, vcc
	ds_read2_b32 v[64:65], v187 offset0:135 offset1:136
	v_cmp_gt_i32_e32 vcc, 26, v181
	v_max3_f32 v66, v66, v193, v192
	s_waitcnt lgkmcnt(0)
	v_pk_add_f32 v[64:65], v[76:77], v[64:65] op_sel:[0,1] op_sel_hi:[1,0]
	s_nop 0
	v_cndmask_b32_e32 v194, v220, v65, vcc
	v_cmp_gt_i32_e32 vcc, 25, v181
	s_nop 1
	v_cndmask_b32_e32 v195, v220, v64, vcc
	ds_read2_b32 v[64:65], v187 offset0:133 offset1:134
	v_cmp_gt_i32_e32 vcc, 28, v181
	v_max3_f32 v66, v66, v195, v194
	s_waitcnt lgkmcnt(0)
	v_pk_add_f32 v[64:65], v[78:79], v[64:65] op_sel:[0,1] op_sel_hi:[1,0]
	s_nop 0
	v_cndmask_b32_e32 v196, v220, v65, vcc
	v_cmp_gt_i32_e32 vcc, 27, v181
	s_nop 1
	v_cndmask_b32_e32 v197, v220, v64, vcc
	v_max3_f32 v202, v66, v197, v196

.LBB0_128:
	v_mov_b32_e32 v100, v213
	v_cvt_pk_bf16_f32 v48, v2, v3
	v_cvt_pk_bf16_f32 v134, v54, v55
	v_bfe_u32 v0, v100, 2, 2
	v_lshrrev_b32_e32 v1, 3, v100
	v_bfe_u32 v2, v100, 1, 1
	v_and_or_b32 v54, v1, 2, v2
	v_lshlrev_b32_e32 v55, 2, v0
	v_lshlrev_b32_e32 v1, 3, v100
	v_or_b32_e32 v151, 16, v180
	v_cvt_pk_bf16_f32 v149, v52, v53
	v_and_b32_e32 v152, 8, v1
	v_or_b32_e32 v52, v55, v226
	v_or_b32_e32 v1, v0, v151
	v_lshlrev_b32_e32 v153, 8, v1
	v_bitop3_b32 v1, v55, v54, v226 bitop3:0x36
	v_or_b32_e32 v0, v0, v180
	v_bitop3_b32 v2, v52, v54, 2 bitop3:0x36
	v_cvt_pk_bf16_f32 v131, v16, v17
	v_cvt_pk_bf16_f32 v132, v18, v19
	v_lshlrev_b32_e32 v53, 8, v0
	v_lshl_add_u32 v16, v1, 4, s80
	v_lshl_add_u32 v18, v2, 4, s80
	v_cvt_pk_bf16_f32 v133, v20, v21
	v_add3_u32 v20, v16, v53, v152
	v_add3_u32 v21, v18, v53, v152
	v_cvt_pk_bf16_f32 v49, v4, v5
	v_cvt_pk_bf16_f32 v50, v6, v7
	v_cvt_pk_bf16_f32 v51, v8, v9
	ds_read_b64_tr_b16 v[0:1], v20
	ds_read_b64_tr_b16 v[2:3], v21 offset:2048
	v_or_b32_e32 v154, 0x800, v153
	v_cvt_pk_bf16_f32 v72, v22, v23
	v_add3_u32 v22, v16, v153, v152
	v_add3_u32 v23, v18, v154, v152
	v_cvt_pk_bf16_f32 v142, v10, v11
	v_cvt_pk_bf16_f32 v143, v12, v13
	v_cvt_pk_bf16_f32 v144, v14, v15
	ds_read_b64_tr_b16 v[16:17], v22
	ds_read_b64_tr_b16 v[18:19], v23
	s_waitcnt lgkmcnt(2)
	v_mfma_f32_32x32x16_bf16 v[0:15], v[48:51], v[0:3], 0
	v_cvt_pk_bf16_f32 v145, v30, v31
	v_cvt_pk_bf16_f32 v146, v64, v65
	v_cvt_pk_bf16_f32 v147, v66, v67
	v_cvt_pk_bf16_f32 v148, v68, v69
	v_cvt_pk_bf16_f32 v135, v56, v57
	v_cvt_pk_bf16_f32 v136, v58, v59
	v_cvt_pk_bf16_f32 v137, v62, v63
	ds_read_b64_tr_b16 v[244:245], v20 offset:8192
	ds_read_b64_tr_b16 v[246:247], v21 offset:10240
	s_waitcnt lgkmcnt(2)
	v_mfma_f32_32x32x16_bf16 v[0:15], v[142:145], v[16:19], v[0:15]
	v_cvt_pk_bf16_f32 v138, v32, v33
	v_cvt_pk_bf16_f32 v139, v34, v35
	v_cvt_pk_bf16_f32 v140, v36, v37
	v_cvt_pk_bf16_f32 v141, v38, v39
	v_cvt_pk_bf16_f32 v76, v40, v41
	v_cvt_pk_bf16_f32 v77, v42, v43
	ds_read_b64_tr_b16 v[16:17], v22 offset:8192
	ds_read_b64_tr_b16 v[18:19], v23 offset:8192
	s_waitcnt lgkmcnt(2)
	v_mfma_f32_32x32x16_bf16 v[0:15], v[146:149], v[244:247], v[0:15]
	v_cvt_pk_bf16_f32 v78, v44, v45
	v_cvt_pk_bf16_f32 v79, v46, v47
	v_cvt_pk_bf16_f32 v130, v60, v61
	v_cvt_pk_bf16_f32 v73, v24, v25
	v_cvt_pk_bf16_f32 v74, v26, v27
	v_cvt_pk_bf16_f32 v75, v28, v29
	ds_read_b64_tr_b16 v[244:245], v20 offset:16384
	ds_read_b64_tr_b16 v[246:247], v21 offset:18432
	s_waitcnt lgkmcnt(2)
	v_mfma_f32_32x32x16_bf16 v[0:15], v[134:137], v[16:19], v[0:15]
	v_cvt_pk_bf16_f32 v68, v70, v178
	v_cvt_pk_bf16_f32 v69, v71, v179
	v_cvt_pk_bf16_f32 v70, v182, v183
	v_cvt_pk_bf16_f32 v71, v184, v185
	v_cvt_pk_bf16_f32 v64, v186, v187
	v_cvt_pk_bf16_f32 v65, v188, v189
	ds_read_b64_tr_b16 v[16:17], v22 offset:16384
	ds_read_b64_tr_b16 v[18:19], v23 offset:16384
	s_waitcnt lgkmcnt(2)
	v_mfma_f32_32x32x16_bf16 v[0:15], v[138:141], v[244:247], v[0:15]
	v_cvt_pk_bf16_f32 v66, v190, v191
	v_cvt_pk_bf16_f32 v67, v192, v193
	s_cmp_lt_i32 s89, 0
	s_cselect_b64 s[28:29], -1, 0
	s_cmp_gt_i32 s89, -1
	s_cselect_b64 s[30:31], -1, 0
	ds_read_b64_tr_b16 v[244:245], v20 offset:24576
	ds_read_b64_tr_b16 v[246:247], v21 offset:26624
	s_waitcnt lgkmcnt(2)
	v_mfma_f32_32x32x16_bf16 v[0:15], v[76:79], v[16:19], v[0:15]
	s_and_b64 vcc, exec, s[28:29]
	ds_read_b64_tr_b16 v[16:17], v22 offset:24576
	ds_read_b64_tr_b16 v[18:19], v23 offset:24576
	s_waitcnt lgkmcnt(2)
	v_mfma_f32_32x32x16_bf16 v[0:15], v[130:133], v[244:247], v[0:15]
	ds_read_b64_tr_b16 v[244:245], v20 offset:32768
	ds_read_b64_tr_b16 v[246:247], v21 offset:34816
	s_waitcnt lgkmcnt(2)
	v_mfma_f32_32x32x16_bf16 v[0:15], v[72:75], v[16:19], v[0:15]
	ds_read_b64_tr_b16 v[16:17], v22 offset:32768
	ds_read_b64_tr_b16 v[18:19], v23 offset:32768
	s_waitcnt lgkmcnt(2)
	v_mfma_f32_32x32x16_bf16 v[0:15], v[68:71], v[244:247], v[0:15]
	s_waitcnt lgkmcnt(0)
	v_mfma_f32_32x32x16_bf16 v[0:15], v[64:67], v[16:19], v[0:15]
	v_or_b32_e32 v18, 4, v54
	v_bitop3_b32 v16, v55, v18, v226 bitop3:0x36
	v_bitop3_b32 v18, v52, v18, 2 bitop3:0x36
	v_lshl_add_u32 v32, v16, 4, s80
	v_lshl_add_u32 v34, v18, 4, s80
	v_add3_u32 v36, v32, v53, v152
	v_add3_u32 v37, v34, v53, v152
	ds_read_b64_tr_b16 v[16:17], v36
	ds_read_b64_tr_b16 v[18:19], v37 offset:2048
	v_add3_u32 v38, v32, v153, v152
	v_add3_u32 v39, v34, v154, v152
	ds_read_b64_tr_b16 v[32:33], v38
	ds_read_b64_tr_b16 v[34:35], v39
	s_waitcnt lgkmcnt(2)
	v_mfma_f32_32x32x16_bf16 v[16:31], v[48:51], v[16:19], 0
	ds_read_b64_tr_b16 v[244:245], v36 offset:8192
	ds_read_b64_tr_b16 v[246:247], v37 offset:10240
	s_waitcnt lgkmcnt(2)
	v_mfma_f32_32x32x16_bf16 v[16:31], v[142:145], v[32:35], v[16:31]
	ds_read_b64_tr_b16 v[32:33], v38 offset:8192
	ds_read_b64_tr_b16 v[34:35], v39 offset:8192
	s_waitcnt lgkmcnt(2)
	v_mfma_f32_32x32x16_bf16 v[16:31], v[146:149], v[244:247], v[16:31]
	ds_read_b64_tr_b16 v[244:245], v36 offset:16384
	ds_read_b64_tr_b16 v[246:247], v37 offset:18432
	s_waitcnt lgkmcnt(2)
	v_mfma_f32_32x32x16_bf16 v[16:31], v[134:137], v[32:35], v[16:31]
	ds_read_b64_tr_b16 v[32:33], v38 offset:16384
	ds_read_b64_tr_b16 v[34:35], v39 offset:16384
	s_waitcnt lgkmcnt(2)
	v_mfma_f32_32x32x16_bf16 v[16:31], v[138:141], v[244:247], v[16:31]
	ds_read_b64_tr_b16 v[244:245], v36 offset:24576
	ds_read_b64_tr_b16 v[246:247], v37 offset:26624
	s_waitcnt lgkmcnt(2)
	v_mfma_f32_32x32x16_bf16 v[16:31], v[76:79], v[32:35], v[16:31]
	ds_read_b64_tr_b16 v[32:33], v38 offset:24576
	ds_read_b64_tr_b16 v[34:35], v39 offset:24576
	s_waitcnt lgkmcnt(2)
	v_mfma_f32_32x32x16_bf16 v[16:31], v[130:133], v[244:247], v[16:31]
	ds_read_b64_tr_b16 v[244:245], v36 offset:32768
	ds_read_b64_tr_b16 v[246:247], v37 offset:34816
	s_waitcnt lgkmcnt(2)
	v_mfma_f32_32x32x16_bf16 v[16:31], v[72:75], v[32:35], v[16:31]
	ds_read_b64_tr_b16 v[32:33], v38 offset:32768
	ds_read_b64_tr_b16 v[34:35], v39 offset:32768
	s_waitcnt lgkmcnt(2)
	v_mfma_f32_32x32x16_bf16 v[16:31], v[68:71], v[244:247], v[16:31]
	s_waitcnt lgkmcnt(0)
	v_mfma_f32_32x32x16_bf16 v[16:31], v[64:67], v[32:35], v[16:31]
	v_or_b32_e32 v34, 8, v54
	v_bitop3_b32 v32, v55, v34, v226 bitop3:0x36
	v_bitop3_b32 v34, v52, v34, 2 bitop3:0x36
	v_lshl_add_u32 v56, v32, 4, s80
	v_lshl_add_u32 v58, v34, 4, s80
	v_add3_u32 v60, v56, v53, v152
	v_add3_u32 v61, v58, v53, v152
	ds_read_b64_tr_b16 v[32:33], v60
	ds_read_b64_tr_b16 v[34:35], v61 offset:2048
	v_add3_u32 v62, v56, v153, v152
	v_add3_u32 v63, v58, v154, v152
	ds_read_b64_tr_b16 v[56:57], v62
	ds_read_b64_tr_b16 v[58:59], v63
	s_waitcnt lgkmcnt(2)
	v_mfma_f32_32x32x16_bf16 v[32:47], v[48:51], v[32:35], 0
	ds_read_b64_tr_b16 v[244:245], v60 offset:8192
	ds_read_b64_tr_b16 v[246:247], v61 offset:10240
	s_waitcnt lgkmcnt(2)
	v_mfma_f32_32x32x16_bf16 v[32:47], v[142:145], v[56:59], v[32:47]
	ds_read_b64_tr_b16 v[56:57], v62 offset:8192
	ds_read_b64_tr_b16 v[58:59], v63 offset:8192
	s_waitcnt lgkmcnt(2)
	v_mfma_f32_32x32x16_bf16 v[32:47], v[146:149], v[244:247], v[32:47]
	ds_read_b64_tr_b16 v[244:245], v60 offset:16384
	ds_read_b64_tr_b16 v[246:247], v61 offset:18432
	s_waitcnt lgkmcnt(2)
	v_mfma_f32_32x32x16_bf16 v[32:47], v[134:137], v[56:59], v[32:47]
	ds_read_b64_tr_b16 v[56:57], v62 offset:16384
	ds_read_b64_tr_b16 v[58:59], v63 offset:16384
	s_waitcnt lgkmcnt(2)
	v_mfma_f32_32x32x16_bf16 v[32:47], v[138:141], v[244:247], v[32:47]
	ds_read_b64_tr_b16 v[244:245], v60 offset:24576
	ds_read_b64_tr_b16 v[246:247], v61 offset:26624
	s_waitcnt lgkmcnt(2)
	v_mfma_f32_32x32x16_bf16 v[32:47], v[76:79], v[56:59], v[32:47]
	ds_read_b64_tr_b16 v[56:57], v62 offset:24576
	ds_read_b64_tr_b16 v[58:59], v63 offset:24576
	s_waitcnt lgkmcnt(2)
	v_mfma_f32_32x32x16_bf16 v[32:47], v[130:133], v[244:247], v[32:47]
	ds_read_b64_tr_b16 v[244:245], v60 offset:32768
	ds_read_b64_tr_b16 v[246:247], v61 offset:34816
	s_waitcnt lgkmcnt(2)
	v_mfma_f32_32x32x16_bf16 v[32:47], v[72:75], v[56:59], v[32:47]
	ds_read_b64_tr_b16 v[56:57], v62 offset:32768
	ds_read_b64_tr_b16 v[58:59], v63 offset:32768
	s_waitcnt lgkmcnt(2)
	v_mfma_f32_32x32x16_bf16 v[32:47], v[68:71], v[244:247], v[32:47]
	s_waitcnt lgkmcnt(0)
	v_mfma_f32_32x32x16_bf16 v[32:47], v[64:67], v[56:59], v[32:47]
	v_or_b32_e32 v56, 12, v54
	v_bitop3_b32 v54, v55, v56, v226 bitop3:0x36
	v_bitop3_b32 v52, v52, v56, 2 bitop3:0x36
	v_lshl_add_u32 v155, v54, 4, s80
	v_lshl_add_u32 v158, v52, 4, s80
	v_add3_u32 v160, v155, v53, v152
	v_add3_u32 v161, v158, v53, v152
	ds_read_b64_tr_b16 v[54:55], v160
	ds_read_b64_tr_b16 v[56:57], v161 offset:2048
	v_add3_u32 v153, v155, v153, v152
	ds_read_b64_tr_b16 v[156:157], v153
	s_waitcnt lgkmcnt(1)
	v_mfma_f32_32x32x16_bf16 v[48:63], v[48:51], v[54:57], 0
	v_add3_u32 v152, v158, v154, v152
	ds_read_b64_tr_b16 v[158:159], v152
	s_waitcnt lgkmcnt(0)
	v_mfma_f32_32x32x16_bf16 v[48:63], v[142:145], v[156:159], v[48:63]
	ds_read_b64_tr_b16 v[142:143], v160 offset:8192
	ds_read_b64_tr_b16 v[144:145], v161 offset:10240
	s_waitcnt lgkmcnt(0)
	v_mfma_f32_32x32x16_bf16 v[48:63], v[146:149], v[142:145], v[48:63]
	ds_read_b64_tr_b16 v[142:143], v153 offset:8192
	ds_read_b64_tr_b16 v[144:145], v152 offset:8192
	s_waitcnt lgkmcnt(0)
	v_mfma_f32_32x32x16_bf16 v[48:63], v[134:137], v[142:145], v[48:63]
	ds_read_b64_tr_b16 v[134:135], v160 offset:16384
	ds_read_b64_tr_b16 v[136:137], v161 offset:18432
	s_waitcnt lgkmcnt(0)
	v_mfma_f32_32x32x16_bf16 v[48:63], v[138:141], v[134:137], v[48:63]
	ds_read_b64_tr_b16 v[134:135], v153 offset:16384
	ds_read_b64_tr_b16 v[136:137], v152 offset:16384
	s_waitcnt lgkmcnt(0)
	v_mfma_f32_32x32x16_bf16 v[48:63], v[76:79], v[134:137], v[48:63]
	ds_read_b64_tr_b16 v[76:77], v160 offset:24576
	ds_read_b64_tr_b16 v[78:79], v161 offset:26624
	s_waitcnt lgkmcnt(0)
	v_mfma_f32_32x32x16_bf16 v[48:63], v[130:133], v[76:79], v[48:63]
	ds_read_b64_tr_b16 v[76:77], v153 offset:24576
	ds_read_b64_tr_b16 v[78:79], v152 offset:24576
	v_ashrrev_i32_e32 v133, 3, v100
	v_lshlrev_b32_e32 v100, 4, v100
	v_and_b32_e32 v100, 0x70, v100
	v_lshl_add_u32 v132, v227, 1, s79
	v_add_u32_e32 v134, s79, v100
	v_lshl_add_u64 v[130:131], s[50:51], 0, v[100:101]
	s_waitcnt lgkmcnt(0)
	v_mfma_f32_32x32x16_bf16 v[48:63], v[72:75], v[76:79], v[48:63]
	ds_read_b64_tr_b16 v[72:73], v160 offset:32768
	ds_read_b64_tr_b16 v[74:75], v161 offset:34816
	v_lshlrev_b32_e32 v100, 9, v226
	v_add_u32_e32 v100, v132, v100
	s_waitcnt lgkmcnt(0)
	v_mfma_f32_32x32x16_bf16 v[48:63], v[68:71], v[72:75], v[48:63]
	ds_read_b64_tr_b16 v[68:69], v153 offset:32768
	ds_read_b64_tr_b16 v[70:71], v152 offset:32768
	s_waitcnt lgkmcnt(0)
	v_mfma_f32_32x32x16_bf16 v[48:63], v[64:67], v[68:71], v[48:63]
	v_lshl_add_u32 v64, v180, 2, s78
	ds_read_b128 v[76:79], v64
	ds_read_b128 v[72:75], v64 offset:32
	ds_read_b128 v[68:71], v64 offset:64
	ds_read_b128 v[64:67], v64 offset:96
	s_waitcnt lgkmcnt(3)
	v_mul_f32_e32 v0, v0, v76
	v_cvt_pk_bf16_f32 v0, v0, s0
	ds_write_b16 v100, v0
	v_mul_f32_e32 v0, v16, v76
	v_cvt_pk_bf16_f32 v0, v0, s0
	ds_write_b16 v100, v0 offset:64
	v_mul_f32_e32 v0, v1, v77
	v_cvt_pk_bf16_f32 v0, v0, s0
	ds_write_b16 v100, v0 offset:128
	v_mul_f32_e32 v0, v17, v77
	v_cvt_pk_bf16_f32 v0, v0, s0
	ds_write_b16 v100, v0 offset:192
	v_mul_f32_e32 v0, v2, v78
	v_cvt_pk_bf16_f32 v0, v0, s0
	ds_write_b16 v100, v0 offset:256
	v_mul_f32_e32 v0, v18, v78
	v_cvt_pk_bf16_f32 v0, v0, s0
	ds_write_b16 v100, v0 offset:320
	v_mul_f32_e32 v0, v3, v79
	v_cvt_pk_bf16_f32 v0, v0, s0
	ds_write_b16 v100, v0 offset:384
	v_mul_f32_e32 v0, v19, v79
	v_cvt_pk_bf16_f32 v0, v0, s0
	ds_write_b16 v100, v0 offset:448
	s_waitcnt lgkmcnt(10)
	v_mul_f32_e32 v0, v4, v72
	v_cvt_pk_bf16_f32 v0, v0, s0
	ds_write_b16 v100, v0 offset:1024
	v_mul_f32_e32 v0, v20, v72
	v_cvt_pk_bf16_f32 v0, v0, s0
	ds_write_b16 v100, v0 offset:1088
	v_mul_f32_e32 v0, v5, v73
	v_cvt_pk_bf16_f32 v0, v0, s0
	ds_write_b16 v100, v0 offset:1152
	v_mul_f32_e32 v0, v21, v73
	v_cvt_pk_bf16_f32 v0, v0, s0
	ds_write_b16 v100, v0 offset:1216
	v_mul_f32_e32 v0, v6, v74
	v_cvt_pk_bf16_f32 v0, v0, s0
	ds_write_b16 v100, v0 offset:1280
	v_mul_f32_e32 v0, v22, v74
	v_cvt_pk_bf16_f32 v0, v0, s0
	ds_write_b16 v100, v0 offset:1344
	v_mul_f32_e32 v0, v7, v75
	v_cvt_pk_bf16_f32 v0, v0, s0
	ds_write_b16 v100, v0 offset:1408
	v_mul_f32_e32 v0, v23, v75
	v_cvt_pk_bf16_f32 v0, v0, s0
	ds_write_b16 v100, v0 offset:1472
	v_lshlrev_b32_e32 v0, 7, v151
	v_add_u32_e32 v5, v132, v0
	s_waitcnt lgkmcnt(14)
	v_mul_f32_e32 v0, v8, v68
	v_cvt_pk_bf16_f32 v0, v0, s0
	ds_write_b16 v5, v0
	v_mul_f32_e32 v0, v24, v68
	v_cvt_pk_bf16_f32 v0, v0, s0
	ds_write_b16 v5, v0 offset:64
	v_mul_f32_e32 v0, v9, v69
	v_cvt_pk_bf16_f32 v0, v0, s0
	ds_write_b16 v100, v0 offset:2176
	v_mul_f32_e32 v0, v25, v69
	v_cvt_pk_bf16_f32 v0, v0, s0
	ds_write_b16 v100, v0 offset:2240
	v_mul_f32_e32 v0, v10, v70
	v_cvt_pk_bf16_f32 v0, v0, s0
	ds_write_b16 v100, v0 offset:2304
	v_mul_f32_e32 v0, v26, v70
	v_cvt_pk_bf16_f32 v0, v0, s0
	ds_write_b16 v100, v0 offset:2368
	v_mul_f32_e32 v0, v11, v71
	v_cvt_pk_bf16_f32 v0, v0, s0
	ds_write_b16 v100, v0 offset:2432
	v_mul_f32_e32 v0, v27, v71
	v_cvt_pk_bf16_f32 v0, v0, s0
	ds_write_b16 v100, v0 offset:2496
	v_mul_f32_e32 v0, v12, v64
	v_cvt_pk_bf16_f32 v0, v0, s0
	ds_write_b16 v100, v0 offset:3072
	v_mul_f32_e32 v0, v28, v64
	v_cvt_pk_bf16_f32 v0, v0, s0
	ds_write_b16 v100, v0 offset:3136
	v_mul_f32_e32 v0, v13, v65
	v_cvt_pk_bf16_f32 v0, v0, s0
	ds_write_b16 v100, v0 offset:3200
	v_mul_f32_e32 v0, v29, v65
	v_cvt_pk_bf16_f32 v0, v0, s0
	ds_write_b16 v100, v0 offset:3264
	v_mul_f32_e32 v0, v14, v66
	v_cvt_pk_bf16_f32 v0, v0, s0
	ds_write_b16 v100, v0 offset:3328
	v_mul_f32_e32 v0, v30, v66
	v_cvt_pk_bf16_f32 v0, v0, s0
	ds_write_b16 v100, v0 offset:3392
	v_mul_f32_e32 v0, v15, v67
	v_cvt_pk_bf16_f32 v0, v0, s0
	ds_write_b16 v100, v0 offset:3456
	v_mul_f32_e32 v0, v31, v67
	v_cvt_pk_bf16_f32 v0, v0, s0
	ds_write_b16 v100, v0 offset:3520
	v_add_u32_e32 v0, s85, v133
	v_add_u32_e32 v1, 8, v133
	v_add_u32_e32 v2, 16, v133
	v_add_u32_e32 v9, 24, v133
	v_lshl_add_u32 v7, v133, 7, v134
	v_mul_lo_u32 v8, v0, s84
	v_add_u32_e32 v6, s85, v1
	v_lshl_add_u32 v4, v1, 7, v134
	v_add_u32_e32 v3, s85, v2
	v_lshl_add_u32 v2, v2, 7, v134
	v_add_u32_e32 v1, s85, v9
	v_lshl_add_u32 v0, v9, 7, v134
	s_cbranch_vccnz .LBB0_130
	ds_read_b128 v[10:13], v7
	v_add_u32_e32 v14, s67, v8
	v_ashrrev_i32_e32 v15, 31, v14
	v_lshlrev_b64 v[14:15], 13, v[14:15]
	v_lshl_add_u64 v[14:15], v[130:131], 0, v[14:15]
	s_waitcnt lgkmcnt(0)
	global_store_dwordx4 v[14:15], v[10:13], off
	v_mul_lo_u32 v9, v6, s84
	ds_read_b128 v[10:13], v4
	v_add_u32_e32 v14, s67, v9
	v_ashrrev_i32_e32 v15, 31, v14
	v_lshlrev_b64 v[14:15], 13, v[14:15]
	v_lshl_add_u64 v[14:15], v[130:131], 0, v[14:15]
	s_waitcnt lgkmcnt(0)
	global_store_dwordx4 v[14:15], v[10:13], off
	v_mul_lo_u32 v9, v3, s84
	ds_read_b128 v[10:13], v2
	v_add_u32_e32 v14, s67, v9
	v_ashrrev_i32_e32 v15, 31, v14
	v_lshlrev_b64 v[14:15], 13, v[14:15]
	v_lshl_add_u64 v[14:15], v[130:131], 0, v[14:15]
	s_waitcnt lgkmcnt(0)
	global_store_dwordx4 v[14:15], v[10:13], off
	v_mul_lo_u32 v9, v1, s84
	ds_read_b128 v[10:13], v0
	v_add_u32_e32 v14, s67, v9
	v_ashrrev_i32_e32 v15, 31, v14
	v_lshlrev_b64 v[14:15], 13, v[14:15]
	v_lshl_add_u64 v[14:15], v[130:131], 0, v[14:15]
	s_waitcnt lgkmcnt(0)
	global_store_dwordx4 v[14:15], v[10:13], off
